# ssmC prompt path: 16 serialized ushort loads batched into one wait
# speedup vs baseline: 1.0044x; 1.0044x over previous
; DI u16 f2bf(float x) { uint32_t u = __float_as_uint(x); u += 0x7fffu + ((u >> 16) & 1u); return (u16)(u >> 16); }
; DI float bf2f(u16 h) { return __uint_as_float(((uint32_t)h) << 16); }
; DI void wave_lds_sync() { asm volatile("s_waitcnt lgkmcnt(0)" ::: "memory"); }
; DI void ssm_unit(const Params& p, int l, int g, int row0, int T, float& hr, float& hi, bool write_y, u16* tile) {
;     ...
;   for (int t = 0; t < T; ++t) {
;     const float br = bf2f(tile[t * 136 + lane]), bi = bf2f(tile[t * 136 + 64 + lane]);
;     const float nhr = fmaf(abr, hr, fmaf(-abi, hi, br));
;     const float nhi = fmaf(abr, hi, fmaf(abi, hr, bi));
;     hr = nhr; hi = nhi;
;     if (write_y) { tile[t * 136 + lane] = f2bf(hr); tile[t * 136 + 64 + lane] = f2bf(hi); }
;   }
;   if (!write_y) return;
;   wave_lds_sync();
;   bf16x8 cm[4];
; #pragma unroll
;   for (int ks = 0; ks < 4; ++ks) cm[ks] = ldg8(((u16*)(p.ws + WS_Cmat)) + ((size_t)lg * 16 + fr) * 128 + ks * 32 + fq * 8);
;   const float dsk = p.d_skip[(size_t)lg * 16 + fr];
;   u16 uv[4][4];
; #pragma unroll
;   for (int mt = 0; mt < 4; ++mt)
; #pragma unroll
;     for (int j = 0; j < 4; ++j) uv[mt][j] = mt < ntile ? ((u16*)(p.ws + WS_U))[(size_t)(row0 + mt * 16 + fq * 4 + j) * 512 + g * 16 + fr] : (u16)0;
.LBB0_254:
	v_add_u32_e32 v5, s50, v4
	s_waitcnt lgkmcnt(0)
	v_lshlrev_b32_e32 v206, 16, v198
	v_lshlrev_b32_e32 v207, 16, v199
	v_lshlrev_b32_e32 v208, 16, v200
	v_lshlrev_b32_e32 v209, 16, v201
	v_lshlrev_b32_e32 v210, 16, v202
	v_lshlrev_b32_e32 v211, 16, v203
	v_lshlrev_b32_e32 v212, 16, v204
	v_lshlrev_b32_e32 v213, 16, v205
	ds_read_u16 v198, v5 offset:1088
	ds_read_u16 v199, v5 offset:1216
	ds_read_u16 v200, v5 offset:1360
	ds_read_u16 v201, v5 offset:1488
	ds_read_u16 v202, v5 offset:1632
	ds_read_u16 v203, v5 offset:1760
	ds_read_u16 v204, v5 offset:1904
	ds_read_u16 v205, v5 offset:2032
	s_addk_i32 s50, 0x440
	s_cmpk_lg_i32 s50, 0x4400
	v_pk_fma_f32 v[206:207], v[54:55], v[56:57], v[206:207] op_sel:[0,1,0] op_sel_hi:[1,0,1]
	s_nop 0
	v_pk_fma_f32 v[6:7], v[2:3], v[56:57], v[206:207]
	s_nop 0
	v_bfe_u32 v8, v6, 16, 1
	v_add3_u32 v8, v6, v8, s94
	ds_write_b16_d16_hi v5, v8
	v_bfe_u32 v9, v7, 16, 1
	v_add3_u32 v9, v7, v9, s94
	ds_write_b16_d16_hi v5, v9 offset:128
	v_pk_fma_f32 v[208:209], v[54:55], v[6:7], v[208:209] op_sel:[0,1,0] op_sel_hi:[1,0,1]
	s_nop 0
	v_pk_fma_f32 v[6:7], v[2:3], v[6:7], v[208:209]
	s_nop 0
	v_bfe_u32 v8, v6, 16, 1
	v_add3_u32 v8, v6, v8, s94
	ds_write_b16_d16_hi v5, v8 offset:272
	v_bfe_u32 v9, v7, 16, 1
	v_add3_u32 v9, v7, v9, s94
	ds_write_b16_d16_hi v5, v9 offset:400
	v_pk_fma_f32 v[210:211], v[54:55], v[6:7], v[210:211] op_sel:[0,1,0] op_sel_hi:[1,0,1]
	s_nop 0
	v_pk_fma_f32 v[6:7], v[2:3], v[6:7], v[210:211]
	s_nop 0
	v_bfe_u32 v8, v6, 16, 1
	v_add3_u32 v8, v6, v8, s94
	ds_write_b16_d16_hi v5, v8 offset:544
	v_bfe_u32 v9, v7, 16, 1
	v_add3_u32 v9, v7, v9, s94
	ds_write_b16_d16_hi v5, v9 offset:672
	v_pk_fma_f32 v[212:213], v[54:55], v[6:7], v[212:213] op_sel:[0,1,0] op_sel_hi:[1,0,1]
	s_nop 0
	v_pk_fma_f32 v[56:57], v[2:3], v[6:7], v[212:213]
	s_nop 0
	v_bfe_u32 v8, v56, 16, 1
	v_add3_u32 v8, v56, v8, s94
	ds_write_b16_d16_hi v5, v8 offset:816
	v_bfe_u32 v9, v57, 16, 1
	v_add3_u32 v9, v57, v9, s94
	ds_write_b16_d16_hi v5, v9 offset:944
	s_cbranch_scc1 .LBB0_254
	v_lshlrev_b64 v[2:3], 12, v[52:53]
	v_lshl_add_u64 v[2:3], s[6:7], 0, v[2:3]
	v_lshlrev_b32_e32 v4, 8, v66
	v_mov_b32_e32 v5, v1
	v_lshlrev_b64 v[6:7], 6, v[52:53]
	v_lshl_add_u64 v[2:3], v[2:3], 0, v[4:5]
	v_lshl_add_u64 v[6:7], s[56:57], 0, v[6:7]
	v_lshlrev_b32_e32 v8, 2, v66
	v_mov_b32_e32 v9, v1
	s_waitcnt lgkmcnt(0)
	v_lshl_add_u64 v[2:3], v[2:3], 0, v[0:1]
	v_lshl_add_u64 v[6:7], v[6:7], 0, v[8:9]
	global_load_dwordx4 v[26:29], v[2:3], off
	global_load_dwordx4 v[22:25], v[2:3], off offset:64
	global_load_dwordx4 v[18:21], v[2:3], off offset:128
	s_nop 0
	global_load_dwordx4 v[2:5], v[2:3], off offset:192
	v_lshlrev_b32_e32 v8, 1, v66
	global_load_dword v65, v[6:7], off
	v_or_b32_e32 v6, v60, v67
	v_ashrrev_i32_e32 v7, 31, v6
	v_lshl_add_u64 v[8:9], v[58:59], 0, v[8:9]
	v_lshlrev_b64 v[10:11], 10, v[6:7]
	v_lshl_add_u64 v[62:63], v[8:9], 0, v[10:11]
	v_or_b32_e32 v10, 1, v6
	v_ashrrev_i32_e32 v11, 31, v10
	v_lshlrev_b64 v[10:11], 10, v[10:11]
	v_lshl_add_u64 v[60:61], v[8:9], 0, v[10:11]
	v_or_b32_e32 v10, 2, v6
	v_ashrrev_i32_e32 v11, 31, v10
	v_lshlrev_b64 v[10:11], 10, v[10:11]
	v_lshl_add_u64 v[58:59], v[8:9], 0, v[10:11]
	v_or_b32_e32 v10, 3, v6
	v_ashrrev_i32_e32 v11, 31, v10
	v_lshlrev_b64 v[10:11], 10, v[10:11]
	v_lshl_add_u64 v[56:57], v[8:9], 0, v[10:11]
	v_or_b32_e32 v10, 16, v6
	v_ashrrev_i32_e32 v11, 31, v10
	v_lshlrev_b64 v[10:11], 10, v[10:11]
	v_lshl_add_u64 v[54:55], v[8:9], 0, v[10:11]
	v_or_b32_e32 v10, 17, v6
	v_ashrrev_i32_e32 v11, 31, v10
	v_lshlrev_b64 v[10:11], 10, v[10:11]
	v_lshl_add_u64 v[52:53], v[8:9], 0, v[10:11]
	v_or_b32_e32 v10, 18, v6
	v_ashrrev_i32_e32 v11, 31, v10
	v_lshlrev_b64 v[10:11], 10, v[10:11]
	v_lshl_add_u64 v[48:49], v[8:9], 0, v[10:11]
	v_or_b32_e32 v10, 19, v6
	v_ashrrev_i32_e32 v11, 31, v10
	v_lshlrev_b64 v[10:11], 10, v[10:11]
	v_lshl_add_u64 v[46:47], v[8:9], 0, v[10:11]
	v_or_b32_e32 v10, 32, v6
	v_ashrrev_i32_e32 v11, 31, v10
	v_lshlrev_b64 v[10:11], 10, v[10:11]
	v_lshl_add_u64 v[44:45], v[8:9], 0, v[10:11]
	v_or_b32_e32 v10, 33, v6
	v_ashrrev_i32_e32 v11, 31, v10
	v_lshlrev_b64 v[10:11], 10, v[10:11]
	v_lshl_add_u64 v[42:43], v[8:9], 0, v[10:11]
	v_or_b32_e32 v10, 34, v6
	v_ashrrev_i32_e32 v11, 31, v10
	v_lshlrev_b64 v[10:11], 10, v[10:11]
	v_lshl_add_u64 v[40:41], v[8:9], 0, v[10:11]
	v_or_b32_e32 v10, 35, v6
	v_ashrrev_i32_e32 v11, 31, v10
	v_lshlrev_b64 v[10:11], 10, v[10:11]
	v_lshl_add_u64 v[38:39], v[8:9], 0, v[10:11]
	v_or_b32_e32 v10, 48, v6
	v_ashrrev_i32_e32 v11, 31, v10
	v_lshlrev_b64 v[10:11], 10, v[10:11]
	v_lshl_add_u64 v[36:37], v[8:9], 0, v[10:11]
	v_or_b32_e32 v10, 49, v6
	v_ashrrev_i32_e32 v11, 31, v10
	v_lshlrev_b64 v[10:11], 10, v[10:11]
	v_lshl_add_u64 v[34:35], v[8:9], 0, v[10:11]
	v_or_b32_e32 v10, 50, v6
	v_ashrrev_i32_e32 v11, 31, v10
	v_lshlrev_b64 v[10:11], 10, v[10:11]
	v_lshl_add_u64 v[32:33], v[8:9], 0, v[10:11]
	v_or_b32_e32 v6, 51, v6
	v_add3_u32 v0, v64, v0, v74
	ds_read_b128 v[10:13], v0 offset:64
	ds_read_b128 v[74:77], v0 offset:8768
	v_ashrrev_i32_e32 v7, 31, v6
	v_lshlrev_b64 v[6:7], 10, v[6:7]
	v_lshl_add_u64 v[30:31], v[8:9], 0, v[6:7]
	global_load_ushort v198, v[44:45], off
	global_load_ushort v199, v[42:43], off
	global_load_ushort v200, v[40:41], off
	global_load_ushort v201, v[38:39], off
	global_load_ushort v202, v[36:37], off
	global_load_ushort v203, v[34:35], off
	global_load_ushort v204, v[32:33], off
	global_load_ushort v205, v[30:31], off
	global_load_ushort v206, v[62:63], off
	global_load_ushort v207, v[60:61], off
	global_load_ushort v208, v[58:59], off
	global_load_ushort v209, v[56:57], off
	global_load_ushort v210, v[54:55], off
	global_load_ushort v211, v[52:53], off
	global_load_ushort v212, v[48:49], off
	global_load_ushort v213, v[46:47], off
	s_waitcnt vmcnt(0) lgkmcnt(0)
; DI u16 f2bf(float x) { uint32_t u = __float_as_uint(x); u += 0x7fffu + ((u >> 16) & 1u); return (u16)(u >> 16); }
; DI float bf2f(u16 h) { return __uint_as_float(((uint32_t)h) << 16); }
; DI float geluf_(float v) { return v * sigmoidf_(1.5957691216f * (v + 0.044715f * v * v * v)); }
; DI f32x4 mfma16(bf16x8 a, bf16x8 b, f32x4 c) { return __builtin_amdgcn_mfma_f32_16x16x32_bf16(a, b, c, 0, 0, 0); }
; DI void ssm_unit(const Params& p, int l, int g, int row0, int T, float& hr, float& hi, bool write_y, u16* tile) {
;     ...
;   bf16x8 cm[4];
; #pragma unroll
;   for (int ks = 0; ks < 4; ++ks) cm[ks] = ldg8(((u16*)(p.ws + WS_Cmat)) + ((size_t)lg * 16 + fr) * 128 + ks * 32 + fq * 8);
;   const float dsk = p.d_skip[(size_t)lg * 16 + fr];
;   u16 uv[4][4];
; #pragma unroll
;   for (int mt = 0; mt < 4; ++mt)
; #pragma unroll
;     for (int j = 0; j < 4; ++j) uv[mt][j] = mt < ntile ? ((u16*)(p.ws + WS_U))[(size_t)(row0 + mt * 16 + fq * 4 + j) * 512 + g * 16 + fr] : (u16)0;
;   f32x4 ya[4];
; #pragma unroll
;   for (int mt = 0; mt < 4; ++mt) {
;     f32x4 a = {0.f, 0.f, 0.f, 0.f};
;     if (mt < ntile) {
; #pragma unroll
;       for (int ks = 0; ks < 4; ++ks) a = mfma16(*reinterpret_cast<const bf16x8*>(tile + (mt * 16 + fr) * 136 + ks * 32 + fq * 8), cm[ks], a);
;     }
;     ya[mt] = a;
;   }
; #pragma unroll
;   for (int mt = 0; mt < 4; ++mt) {
;     if (mt < ntile) {
; #pragma unroll
;       for (int j = 0; j < 4; ++j) {
;         u16* up = ((u16*)(p.ws + WS_U)) + (size_t)(row0 + mt * 16 + fq * 4 + j) * 512 + g * 16 + fr;
;         const float y = ya[mt][j] + dsk * bf2f(uv[mt][j]);
;         *up = f2bf(geluf_(y));
;       }
;     }
;   }
	v_lshlrev_b32_e32 v73, 16, v198
	v_lshlrev_b32_e32 v72, 16, v199
	v_lshlrev_b32_e32 v71, 16, v200
	v_lshlrev_b32_e32 v70, 16, v201
	v_lshlrev_b32_e32 v69, 16, v202
	v_lshlrev_b32_e32 v68, 16, v203
	v_lshlrev_b32_e32 v67, 16, v204
	v_lshlrev_b32_e32 v66, 16, v205
	ds_read_b128 v[6:9], v0
	s_waitcnt lgkmcnt(0)
	v_mfma_f32_16x16x32_bf16 v[6:9], v[6:9], v[26:29], 0
	v_mfma_f32_16x16x32_bf16 v[6:9], v[10:13], v[22:25], v[6:9]
	ds_read_b128 v[10:13], v0 offset:128
	s_waitcnt lgkmcnt(0)
	v_mfma_f32_16x16x32_bf16 v[6:9], v[10:13], v[18:21], v[6:9]
	ds_read_b128 v[10:13], v0 offset:192
	s_waitcnt lgkmcnt(0)
	v_mfma_f32_16x16x32_bf16 v[14:17], v[10:13], v[2:5], v[6:9]
	s_nop 4
	ds_read_b128 v[6:9], v0 offset:4352
	ds_read_b128 v[10:13], v0 offset:4416
	s_waitcnt lgkmcnt(1)
	v_mfma_f32_16x16x32_bf16 v[6:9], v[6:9], v[26:29], 0
	s_waitcnt lgkmcnt(0)
	v_mfma_f32_16x16x32_bf16 v[6:9], v[10:13], v[22:25], v[6:9]
	ds_read_b128 v[10:13], v0 offset:4480
	s_waitcnt lgkmcnt(0)
	v_mfma_f32_16x16x32_bf16 v[6:9], v[10:13], v[18:21], v[6:9]
	ds_read_b128 v[10:13], v0 offset:4544
	s_waitcnt lgkmcnt(0)
	v_mfma_f32_16x16x32_bf16 v[10:13], v[10:13], v[2:5], v[6:9]
	s_nop 4
	ds_read_b128 v[6:9], v0 offset:8704
	s_waitcnt lgkmcnt(0)
	v_mfma_f32_16x16x32_bf16 v[6:9], v[6:9], v[26:29], 0
	v_mfma_f32_16x16x32_bf16 v[6:9], v[74:77], v[22:25], v[6:9]
	ds_read_b128 v[74:77], v0 offset:8832
	s_waitcnt lgkmcnt(0)
	v_mfma_f32_16x16x32_bf16 v[6:9], v[74:77], v[18:21], v[6:9]
	ds_read_b128 v[74:77], v0 offset:8896
	s_waitcnt lgkmcnt(0)
	v_mfma_f32_16x16x32_bf16 v[6:9], v[74:77], v[2:5], v[6:9]
	ds_read_b128 v[74:77], v0 offset:13056
	s_nop 6
	v_fmac_f32_e32 v9, v65, v70
	s_waitcnt lgkmcnt(0)
	v_mfma_f32_16x16x32_bf16 v[26:29], v[74:77], v[26:29], 0
	ds_read_b128 v[74:77], v0 offset:13120
	s_waitcnt lgkmcnt(0)
	v_mfma_f32_16x16x32_bf16 v[22:25], v[74:77], v[22:25], v[26:29]
	s_nop 4
	ds_read_b128 v[26:29], v0 offset:13184
	s_waitcnt lgkmcnt(0)
	v_mfma_f32_16x16x32_bf16 v[18:21], v[26:29], v[18:21], v[22:25]
	s_nop 2
	ds_read_b128 v[22:25], v0 offset:13248
	v_mov_b32_e32 v0, v206
	s_waitcnt vmcnt(0) lgkmcnt(0)
	v_lshlrev_b32_e32 v0, 16, v0
	v_fma_f32 v0, v65, v0, v14
	v_mul_f32_e32 v14, 0x3d372713, v0
	v_mul_f32_e32 v14, v0, v14
	v_fma_f32 v14, v0, v14, v0
	v_mul_f32_e32 v14, 0x3fcc422a, v14
	v_mul_f32_e32 v14, 0xbfb8aa3b, v14
	v_exp_f32_e32 v14, v14
	v_mfma_f32_16x16x32_bf16 v[2:5], v[22:25], v[2:5], v[18:21]
	v_add_f32_e32 v14, 1.0, v14
	s_nop 1
	v_div_scale_f32 v18, s[48:49], v14, v14, 1.0
	v_rcp_f32_e32 v19, v18
	s_nop 2
	v_fmac_f32_e32 v5, v65, v66
	v_fma_f32 v20, -v18, v19, 1.0
	v_fmac_f32_e32 v19, v20, v19
	v_div_scale_f32 v20, vcc, 1.0, v14, 1.0
	v_mul_f32_e32 v21, v20, v19
	v_fma_f32 v22, -v18, v21, v20
	v_fmac_f32_e32 v21, v22, v19
	v_fma_f32 v18, -v18, v21, v20
	v_div_fmas_f32 v18, v18, v19, v21
	v_div_fixup_f32 v14, v18, v14, 1.0
	v_mul_f32_e32 v0, v0, v14
	v_bfe_u32 v14, v0, 16, 1
	v_add3_u32 v14, v0, v14, s94
	v_mov_b32_e32 v18, v207
	v_mov_b32_e32 v19, v208
	v_mov_b32_e32 v20, v209
	v_mov_b32_e32 v21, v210
	v_mov_b32_e32 v22, v211
	v_mov_b32_e32 v23, v212
	v_mov_b32_e32 v0, v213
	s_waitcnt vmcnt(0) lgkmcnt(0)
	v_lshlrev_b32_e32 v0, 16, v0
	global_store_short_d16_hi v[62:63], v14, off
	v_lshlrev_b32_e32 v14, 16, v18
	v_fma_f32 v14, v65, v14, v15
	v_mul_f32_e32 v15, 0x3d372713, v14
	v_mul_f32_e32 v15, v14, v15
	v_fma_f32 v15, v14, v15, v14
	v_mul_f32_e32 v15, 0x3fcc422a, v15
	v_mul_f32_e32 v15, 0xbfb8aa3b, v15
	v_exp_f32_e32 v15, v15
	v_fmac_f32_e32 v13, v65, v0
	v_mul_f32_e32 v0, 0x3d372713, v13
	v_mul_f32_e32 v0, v13, v0
	v_add_f32_e32 v15, 1.0, v15
	v_div_scale_f32 v18, s[48:49], v15, v15, 1.0
	v_rcp_f32_e32 v24, v18
	v_fma_f32 v0, v13, v0, v13
	v_mul_f32_e32 v0, 0x3fcc422a, v0
	v_mul_f32_e32 v0, 0xbfb8aa3b, v0
	v_fma_f32 v25, -v18, v24, 1.0
	v_fmac_f32_e32 v24, v25, v24
	v_div_scale_f32 v25, vcc, 1.0, v15, 1.0
	v_mul_f32_e32 v26, v25, v24
	v_fma_f32 v27, -v18, v26, v25
	v_fmac_f32_e32 v26, v27, v24
	v_fma_f32 v18, -v18, v26, v25
	v_div_fmas_f32 v18, v18, v24, v26
	v_div_fixup_f32 v15, v18, v15, 1.0
	v_mul_f32_e32 v14, v14, v15
	v_bfe_u32 v15, v14, 16, 1
	v_add3_u32 v14, v14, v15, s94
	global_store_short_d16_hi v[60:61], v14, off
	v_lshlrev_b32_e32 v14, 16, v19
	v_fma_f32 v14, v65, v14, v16
	v_mul_f32_e32 v15, 0x3d372713, v14
	v_mul_f32_e32 v15, v14, v15
	v_fma_f32 v15, v14, v15, v14
	v_mul_f32_e32 v15, 0x3fcc422a, v15
	v_mul_f32_e32 v15, 0xbfb8aa3b, v15
	v_exp_f32_e32 v15, v15
	v_exp_f32_e32 v0, v0
	v_add_f32_e32 v15, 1.0, v15
	v_div_scale_f32 v16, s[48:49], v15, v15, 1.0
	v_rcp_f32_e32 v18, v16
	v_add_f32_e32 v0, 1.0, v0
	v_fma_f32 v19, -v16, v18, 1.0
	v_fmac_f32_e32 v18, v19, v18
	v_div_scale_f32 v19, vcc, 1.0, v15, 1.0
	v_mul_f32_e32 v24, v19, v18
	v_fma_f32 v25, -v16, v24, v19
	v_fmac_f32_e32 v24, v25, v18
	v_fma_f32 v16, -v16, v24, v19
	v_div_fmas_f32 v16, v16, v18, v24
	v_div_fixup_f32 v15, v16, v15, 1.0
	v_mul_f32_e32 v14, v14, v15
	v_bfe_u32 v15, v14, 16, 1
	v_add3_u32 v14, v14, v15, s94
	global_store_short_d16_hi v[58:59], v14, off
	v_lshlrev_b32_e32 v14, 16, v20
	v_fmac_f32_e32 v17, v65, v14
	v_mul_f32_e32 v14, 0x3d372713, v17
	v_mul_f32_e32 v14, v17, v14
	v_fma_f32 v14, v17, v14, v17
	v_mul_f32_e32 v14, 0x3fcc422a, v14
	v_mul_f32_e32 v14, 0xbfb8aa3b, v14
	v_exp_f32_e32 v14, v14
	s_nop 0
	v_add_f32_e32 v14, 1.0, v14
	v_div_scale_f32 v15, s[48:49], v14, v14, 1.0
	v_rcp_f32_e32 v16, v15
	s_nop 0
	v_fma_f32 v18, -v15, v16, 1.0
	v_fmac_f32_e32 v16, v18, v16
	v_div_scale_f32 v18, vcc, 1.0, v14, 1.0
	v_mul_f32_e32 v19, v18, v16
	v_fma_f32 v20, -v15, v19, v18
	v_fmac_f32_e32 v19, v20, v16
	v_fma_f32 v15, -v15, v19, v18
	v_div_fmas_f32 v15, v15, v16, v19
; DI u16 f2bf(float x) { uint32_t u = __float_as_uint(x); u += 0x7fffu + ((u >> 16) & 1u); return (u16)(u >> 16); }
; DI float bf2f(u16 h) { return __uint_as_float(((uint32_t)h) << 16); }
; DI float geluf_(float v) { return v * sigmoidf_(1.5957691216f * (v + 0.044715f * v * v * v)); }
; DI void ssm_unit(const Params& p, int l, int g, int row0, int T, float& hr, float& hi, bool write_y, u16* tile) {
;     ...
;   for (int mt = 0; mt < 4; ++mt) {
;     if (mt < ntile) {
; #pragma unroll
;       for (int j = 0; j < 4; ++j) {
;         u16* up = ((u16*)(p.ws + WS_U)) + (size_t)(row0 + mt * 16 + fq * 4 + j) * 512 + g * 16 + fr;
;         const float y = ya[mt][j] + dsk * bf2f(uv[mt][j]);
;         *up = f2bf(geluf_(y));
;       }
;     }
;   }
	v_div_fixup_f32 v14, v15, v14, 1.0
	v_mul_f32_e32 v14, v17, v14
	v_bfe_u32 v15, v14, 16, 1
	v_add3_u32 v14, v14, v15, s94
	global_store_short_d16_hi v[56:57], v14, off
	v_lshlrev_b32_e32 v14, 16, v21
	v_fma_f32 v10, v65, v14, v10
	v_mul_f32_e32 v14, 0x3d372713, v10
	v_mul_f32_e32 v14, v10, v14
	v_fma_f32 v14, v10, v14, v10
	v_mul_f32_e32 v14, 0x3fcc422a, v14
	v_mul_f32_e32 v14, 0xbfb8aa3b, v14
	v_exp_f32_e32 v14, v14
	s_nop 0
	v_add_f32_e32 v14, 1.0, v14
	v_div_scale_f32 v15, s[48:49], v14, v14, 1.0
	v_rcp_f32_e32 v16, v15
	s_nop 0
	v_fma_f32 v17, -v15, v16, 1.0
	v_fmac_f32_e32 v16, v17, v16
	v_div_scale_f32 v17, vcc, 1.0, v14, 1.0
	v_mul_f32_e32 v18, v17, v16
	v_fma_f32 v19, -v15, v18, v17
	v_fmac_f32_e32 v18, v19, v16
	v_fma_f32 v15, -v15, v18, v17
	v_div_fmas_f32 v15, v15, v16, v18
	v_div_fixup_f32 v14, v15, v14, 1.0
	v_mul_f32_e32 v10, v10, v14
	v_bfe_u32 v14, v10, 16, 1
	v_add3_u32 v10, v10, v14, s94
	global_store_short_d16_hi v[54:55], v10, off
	v_lshlrev_b32_e32 v10, 16, v22
	v_fma_f32 v10, v65, v10, v11
	v_mul_f32_e32 v11, 0x3d372713, v10
	v_mul_f32_e32 v11, v10, v11
	v_fma_f32 v11, v10, v11, v10
	v_mul_f32_e32 v11, 0x3fcc422a, v11
	v_mul_f32_e32 v11, 0xbfb8aa3b, v11
	v_exp_f32_e32 v11, v11
	s_nop 0
	v_add_f32_e32 v11, 1.0, v11
	v_div_scale_f32 v14, s[48:49], v11, v11, 1.0
	v_rcp_f32_e32 v15, v14
	s_nop 0
	v_fma_f32 v16, -v14, v15, 1.0
	v_fmac_f32_e32 v15, v16, v15
	v_div_scale_f32 v16, vcc, 1.0, v11, 1.0
	v_mul_f32_e32 v17, v16, v15
	v_fma_f32 v18, -v14, v17, v16
	v_fmac_f32_e32 v17, v18, v15
	v_fma_f32 v14, -v14, v17, v16
	v_div_fmas_f32 v14, v14, v15, v17
	v_div_fixup_f32 v11, v14, v11, 1.0
	v_mul_f32_e32 v10, v10, v11
	v_bfe_u32 v11, v10, 16, 1
	v_add3_u32 v10, v10, v11, s94
	global_store_short_d16_hi v[52:53], v10, off
	v_lshlrev_b32_e32 v10, 16, v23
	v_fma_f32 v10, v65, v10, v12
	v_mul_f32_e32 v11, 0x3d372713, v10
	v_mul_f32_e32 v11, v10, v11
	v_fma_f32 v11, v10, v11, v10
	v_mul_f32_e32 v11, 0x3fcc422a, v11
	v_mul_f32_e32 v11, 0xbfb8aa3b, v11
	v_exp_f32_e32 v11, v11
	s_nop 0
	v_add_f32_e32 v11, 1.0, v11
	v_div_scale_f32 v12, s[48:49], v11, v11, 1.0
	v_rcp_f32_e32 v14, v12
	s_nop 0
	v_fma_f32 v15, -v12, v14, 1.0
	v_fmac_f32_e32 v14, v15, v14
	v_div_scale_f32 v15, vcc, 1.0, v11, 1.0
	v_mul_f32_e32 v16, v15, v14
	v_fma_f32 v17, -v12, v16, v15
	v_fmac_f32_e32 v16, v17, v14
	v_fma_f32 v12, -v12, v16, v15
	v_div_fmas_f32 v12, v12, v14, v16
	v_div_fixup_f32 v11, v12, v11, 1.0
	v_mul_f32_e32 v10, v10, v11
	v_bfe_u32 v11, v10, 16, 1
	v_add3_u32 v10, v10, v11, s94
	global_store_short_d16_hi v[48:49], v10, off
	v_div_scale_f32 v10, s[48:49], v0, v0, 1.0
	v_rcp_f32_e32 v11, v10
	s_nop 0
	v_fma_f32 v12, -v10, v11, 1.0
	v_fmac_f32_e32 v11, v12, v11
	v_div_scale_f32 v12, vcc, 1.0, v0, 1.0
	v_mul_f32_e32 v14, v12, v11
	v_fma_f32 v15, -v10, v14, v12
	v_fmac_f32_e32 v14, v15, v11
	v_fma_f32 v10, -v10, v14, v12
	v_div_fmas_f32 v10, v10, v11, v14
	v_div_fixup_f32 v0, v10, v0, 1.0
	v_mul_f32_e32 v0, v13, v0
	v_bfe_u32 v10, v0, 16, 1
	v_add3_u32 v0, v0, v10, s94
	global_store_short_d16_hi v[46:47], v0, off
	v_fma_f32 v0, v65, v73, v6
	v_mul_f32_e32 v6, 0x3d372713, v0
	v_mul_f32_e32 v6, v0, v6
	v_fma_f32 v6, v0, v6, v0
	v_mul_f32_e32 v6, 0x3fcc422a, v6
	v_mul_f32_e32 v6, 0xbfb8aa3b, v6
	v_exp_f32_e32 v6, v6
	s_nop 0
	v_add_f32_e32 v6, 1.0, v6
	v_div_scale_f32 v10, s[48:49], v6, v6, 1.0
	v_rcp_f32_e32 v11, v10
	s_nop 0
	v_fma_f32 v12, -v10, v11, 1.0
	v_fmac_f32_e32 v11, v12, v11
	v_div_scale_f32 v12, vcc, 1.0, v6, 1.0
	v_mul_f32_e32 v13, v12, v11
	v_fma_f32 v14, -v10, v13, v12
	v_fmac_f32_e32 v13, v14, v11
	v_fma_f32 v10, -v10, v13, v12
	v_div_fmas_f32 v10, v10, v11, v13
	v_div_fixup_f32 v6, v10, v6, 1.0
	v_mul_f32_e32 v0, v0, v6
	v_bfe_u32 v6, v0, 16, 1
	v_add3_u32 v0, v0, v6, s94
	global_store_short_d16_hi v[44:45], v0, off
	v_fma_f32 v0, v65, v72, v7
	v_mul_f32_e32 v6, 0x3d372713, v0
	v_mul_f32_e32 v6, v0, v6
	v_fma_f32 v6, v0, v6, v0
	v_mul_f32_e32 v6, 0x3fcc422a, v6
	v_mul_f32_e32 v6, 0xbfb8aa3b, v6
	v_exp_f32_e32 v6, v6
	s_nop 0
	v_add_f32_e32 v6, 1.0, v6
	v_div_scale_f32 v7, s[48:49], v6, v6, 1.0
	v_rcp_f32_e32 v10, v7
	s_nop 0
	v_fma_f32 v11, -v7, v10, 1.0
	v_fmac_f32_e32 v10, v11, v10
	v_div_scale_f32 v11, vcc, 1.0, v6, 1.0
	v_mul_f32_e32 v12, v11, v10
	v_fma_f32 v13, -v7, v12, v11
	v_fmac_f32_e32 v12, v13, v10
	v_fma_f32 v7, -v7, v12, v11
	v_div_fmas_f32 v7, v7, v10, v12
; DI u16 f2bf(float x) { uint32_t u = __float_as_uint(x); u += 0x7fffu + ((u >> 16) & 1u); return (u16)(u >> 16); }
; DI float bf2f(u16 h) { return __uint_as_float(((uint32_t)h) << 16); }
; DI float geluf_(float v) { return v * sigmoidf_(1.5957691216f * (v + 0.044715f * v * v * v)); }
; DI void ssm_unit(const Params& p, int l, int g, int row0, int T, float& hr, float& hi, bool write_y, u16* tile) {
;     ...
;   for (int mt = 0; mt < 4; ++mt) {
;     if (mt < ntile) {
; #pragma unroll
;       for (int j = 0; j < 4; ++j) {
;         u16* up = ((u16*)(p.ws + WS_U)) + (size_t)(row0 + mt * 16 + fq * 4 + j) * 512 + g * 16 + fr;
;         const float y = ya[mt][j] + dsk * bf2f(uv[mt][j]);
;         *up = f2bf(geluf_(y));
;       }
;     }
;   }
	v_div_fixup_f32 v6, v7, v6, 1.0
	v_mul_f32_e32 v0, v0, v6
	v_bfe_u32 v6, v0, 16, 1
	v_add3_u32 v0, v0, v6, s94
	global_store_short_d16_hi v[42:43], v0, off
	v_fma_f32 v0, v65, v71, v8
	v_mul_f32_e32 v6, 0x3d372713, v0
	v_mul_f32_e32 v6, v0, v6
	v_fma_f32 v6, v0, v6, v0
	v_mul_f32_e32 v6, 0x3fcc422a, v6
	v_mul_f32_e32 v6, 0xbfb8aa3b, v6
	v_exp_f32_e32 v6, v6
	s_nop 0
	v_add_f32_e32 v6, 1.0, v6
	v_div_scale_f32 v7, s[48:49], v6, v6, 1.0
	v_rcp_f32_e32 v8, v7
	s_nop 0
	v_fma_f32 v10, -v7, v8, 1.0
	v_fmac_f32_e32 v8, v10, v8
	v_div_scale_f32 v10, vcc, 1.0, v6, 1.0
	v_mul_f32_e32 v11, v10, v8
	v_fma_f32 v12, -v7, v11, v10
	v_fmac_f32_e32 v11, v12, v8
	v_fma_f32 v7, -v7, v11, v10
	v_div_fmas_f32 v7, v7, v8, v11
	v_div_fixup_f32 v6, v7, v6, 1.0
	v_mul_f32_e32 v0, v0, v6
	v_bfe_u32 v6, v0, 16, 1
	v_add3_u32 v0, v0, v6, s94
	global_store_short_d16_hi v[40:41], v0, off
	v_mul_f32_e32 v0, 0x3d372713, v9
	v_mul_f32_e32 v0, v9, v0
	v_fma_f32 v0, v9, v0, v9
	v_mul_f32_e32 v0, 0x3fcc422a, v0
	v_mul_f32_e32 v0, 0xbfb8aa3b, v0
	v_exp_f32_e32 v0, v0
	s_nop 0
	v_add_f32_e32 v0, 1.0, v0
	v_div_scale_f32 v6, s[48:49], v0, v0, 1.0
	v_rcp_f32_e32 v7, v6
	s_nop 0
	v_fma_f32 v8, -v6, v7, 1.0
	v_fmac_f32_e32 v7, v8, v7
	v_div_scale_f32 v8, vcc, 1.0, v0, 1.0
	v_mul_f32_e32 v10, v8, v7
	v_fma_f32 v11, -v6, v10, v8
	v_fmac_f32_e32 v10, v11, v7
	v_fma_f32 v6, -v6, v10, v8
	v_div_fmas_f32 v6, v6, v7, v10
	v_div_fixup_f32 v0, v6, v0, 1.0
	v_mul_f32_e32 v0, v9, v0
	v_bfe_u32 v6, v0, 16, 1
	v_add3_u32 v0, v0, v6, s94
	global_store_short_d16_hi v[38:39], v0, off
	v_fma_f32 v0, v65, v69, v2
	v_mul_f32_e32 v2, 0x3d372713, v0
	v_mul_f32_e32 v2, v0, v2
	v_fma_f32 v2, v0, v2, v0
	v_mul_f32_e32 v2, 0x3fcc422a, v2
	v_mul_f32_e32 v2, 0xbfb8aa3b, v2
	v_exp_f32_e32 v2, v2
	s_nop 0
	v_add_f32_e32 v2, 1.0, v2
	v_div_scale_f32 v6, s[48:49], v2, v2, 1.0
	v_rcp_f32_e32 v7, v6
	s_nop 0
	v_fma_f32 v8, -v6, v7, 1.0
	v_fmac_f32_e32 v7, v8, v7
	v_div_scale_f32 v8, vcc, 1.0, v2, 1.0
	v_mul_f32_e32 v9, v8, v7
	v_fma_f32 v10, -v6, v9, v8
	v_fmac_f32_e32 v9, v10, v7
	v_fma_f32 v6, -v6, v9, v8
	v_div_fmas_f32 v6, v6, v7, v9
	v_div_fixup_f32 v2, v6, v2, 1.0
	v_mul_f32_e32 v0, v0, v2
	v_bfe_u32 v2, v0, 16, 1
	v_add3_u32 v0, v0, v2, s94
	global_store_short_d16_hi v[36:37], v0, off
	v_fma_f32 v0, v65, v68, v3
	v_mul_f32_e32 v2, 0x3d372713, v0
	v_mul_f32_e32 v2, v0, v2
	v_fma_f32 v2, v0, v2, v0
	v_mul_f32_e32 v2, 0x3fcc422a, v2
	v_mul_f32_e32 v2, 0xbfb8aa3b, v2
	v_exp_f32_e32 v2, v2
	s_nop 0
	v_add_f32_e32 v2, 1.0, v2
	v_div_scale_f32 v3, s[48:49], v2, v2, 1.0
	v_rcp_f32_e32 v6, v3
	s_nop 0
	v_fma_f32 v7, -v3, v6, 1.0
	v_fmac_f32_e32 v6, v7, v6
	v_div_scale_f32 v7, vcc, 1.0, v2, 1.0
	v_mul_f32_e32 v8, v7, v6
	v_fma_f32 v9, -v3, v8, v7
	v_fmac_f32_e32 v8, v9, v6
	v_fma_f32 v3, -v3, v8, v7
	v_div_fmas_f32 v3, v3, v6, v8
	v_div_fixup_f32 v2, v3, v2, 1.0
	v_mul_f32_e32 v0, v0, v2
	v_bfe_u32 v2, v0, 16, 1
	v_add3_u32 v0, v0, v2, s94
	global_store_short_d16_hi v[34:35], v0, off
	v_fma_f32 v0, v65, v67, v4
	v_mul_f32_e32 v2, 0x3d372713, v0
	v_mul_f32_e32 v2, v0, v2
	v_fma_f32 v2, v0, v2, v0
	v_mul_f32_e32 v2, 0x3fcc422a, v2
	v_mul_f32_e32 v2, 0xbfb8aa3b, v2
	v_exp_f32_e32 v2, v2
	s_nop 0
	v_add_f32_e32 v2, 1.0, v2
	v_div_scale_f32 v3, s[48:49], v2, v2, 1.0
	v_rcp_f32_e32 v4, v3
	s_nop 0
	v_fma_f32 v6, -v3, v4, 1.0
	v_fmac_f32_e32 v4, v6, v4
	v_div_scale_f32 v6, vcc, 1.0, v2, 1.0
	v_mul_f32_e32 v7, v6, v4
	v_fma_f32 v8, -v3, v7, v6
	v_fmac_f32_e32 v7, v8, v4
	v_fma_f32 v3, -v3, v7, v6
	v_div_fmas_f32 v3, v3, v4, v7
	v_div_fixup_f32 v2, v3, v2, 1.0
	v_mul_f32_e32 v0, v0, v2
	v_bfe_u32 v2, v0, 16, 1
	v_add3_u32 v0, v0, v2, s94
	global_store_short_d16_hi v[32:33], v0, off
	v_mul_f32_e32 v0, 0x3d372713, v5
	v_mul_f32_e32 v0, v5, v0
	v_fma_f32 v0, v5, v0, v5
	v_mul_f32_e32 v0, 0x3fcc422a, v0
	v_mul_f32_e32 v0, 0xbfb8aa3b, v0
	v_exp_f32_e32 v0, v0
	s_nop 0
	v_add_f32_e32 v0, 1.0, v0
	v_div_scale_f32 v2, s[48:49], v0, v0, 1.0
	v_rcp_f32_e32 v3, v2
	s_nop 0
	v_fma_f32 v4, -v2, v3, 1.0
	v_fmac_f32_e32 v3, v4, v3
	v_div_scale_f32 v4, vcc, 1.0, v0, 1.0
	v_mul_f32_e32 v6, v4, v3
	v_fma_f32 v7, -v2, v6, v4
	v_fmac_f32_e32 v6, v7, v3
	v_fma_f32 v2, -v2, v6, v4
	v_div_fmas_f32 v2, v2, v3, v6
	v_div_fixup_f32 v0, v2, v0, 1.0
	v_mul_f32_e32 v0, v5, v0
	v_bfe_u32 v2, v0, 16, 1
	v_add3_u32 v0, v0, v2, s94
	global_store_short_d16_hi v[30:31], v0, off
	s_waitcnt lgkmcnt(0)
	s_branch .LBB0_203
